# v3 + latent DeltaNet scans steered onto paired CUs (designated block ranks pop the work queue first)
# baseline (speedup 1.0000x reference)
.LBB0_184:
	v_readlane_b32 s1, v254, 59
	s_andn2_b64 vcc, exec, s[40:41]
	s_mov_b32 s40, s1
	v_readlane_b32 s1, v254, 58
	s_mov_b32 s42, s1
	s_cbranch_vccnz .LBB0_834
	v_readlane_b32 s1, v255, 2
	s_cmp_lt_i32 s1, 2
	s_mov_b64 s[36:37], -1
	s_cbranch_scc1 .LBB0_614
	v_readlane_b32 s1, v255, 2
	s_cmp_lt_i32 s1, 3
	s_cbranch_scc1 .LBB0_565
	v_readlane_b32 s2, v254, 61
	v_readlane_b32 s3, v254, 62
	s_lshl_b32 s2, s2, 4
	v_writelane_b32 v255, s2, 3
	s_nop 1
	v_writelane_b32 v255, s3, 4
	s_nop 0
	v_readlane_b32 s1, v255, 2
	s_cmp_gt_i32 s1, 3
	s_cbranch_scc0 .LBB0_345
	v_readlane_b32 s0, v255, 3
	v_readlane_b32 s1, v255, 4
	s_mov_b32 s2, s0
	s_ashr_i32 s3, s0, 31
	v_writelane_b32 v255, s0, 3
	s_lshl_b64 s[20:21], s[2:3], 2
	v_readlane_b32 s36, v250, 33
	v_writelane_b32 v255, s1, 4
	v_readlane_b32 s0, v252, 39
	s_add_u32 s2, s0, s20
	v_readlane_b32 s0, v252, 40
	s_addc_u32 s3, s0, s21
	v_writelane_b32 v255, s2, 5
	v_readlane_b32 s0, v254, 61
	v_readlane_b32 s50, v250, 47
	v_writelane_b32 v255, s3, 6
	s_mul_i32 s3, s0, 0xb00000
	s_mul_hi_i32 s2, s0, 0xb00000
	v_readlane_b32 s51, v250, 48
	s_add_u32 s93, s50, s3
	v_readlane_b32 s48, v250, 45
	s_addc_u32 s59, s51, s2
	v_readlane_b32 s49, v250, 46
	s_add_u32 s0, s48, s3
	v_readlane_b32 s46, v250, 43
	v_writelane_b32 v255, s0, 7
	s_addc_u32 s0, s49, s2
	v_readlane_b32 s47, v250, 44
	v_writelane_b32 v255, s0, 8
	s_add_u32 s90, s46, s3
	s_addc_u32 s91, s47, s2
	v_writelane_b32 v255, s59, 9
	v_readlane_b32 s1, v254, 62
	v_readlane_b32 s37, v250, 34
	v_readlane_b32 s38, v250, 35
	v_readlane_b32 s39, v250, 36
	v_readlane_b32 s40, v250, 37
	v_readlane_b32 s41, v250, 38
	v_readlane_b32 s42, v250, 39
	v_readlane_b32 s43, v250, 40
	v_readlane_b32 s44, v250, 41
	v_readlane_b32 s45, v250, 42
	v_readlane_b32 s0, v250, 0
	s_lshr_b32 s0, s0, 3
	s_and_b32 s0, s0, 31
	s_cmp_lt_u32 s0, 4
	s_cbranch_scc1 .Lmix_first_pop
	s_sleep 80
.Lmix_first_pop:
	s_branch .LBB0_191
